# attention loop: one static s_setprio 1 for waves 0-3 instead of waves 4-7, reset after the loop
# baseline (speedup 1.0000x reference)
.LBB0_428:
	s_ashr_i32 s0, s18, 6
	s_add_i32 s4, s0, s19
	s_ashr_i32 s16, s4, 2
	v_mov_b32_e32 v132, v188
	s_ashr_i32 s17, s16, 31
	v_readfirstlane_b32 s34, v132
	s_lshl_b32 s5, s18, 7
	s_bfe_u32 s31, s34, 0x20006
	s_lshl_b64 s[2:3], s[16:17], 13
	s_and_b32 s0, s5, 0x1f80
	s_or_b32 s0, s2, s0
	s_lshl_b32 s2, s31, 5
	v_and_b32_e32 v202, 31, v132
	s_or_b32 s0, s0, s2
	v_or_b32_e32 v176, s0, v202
	v_mad_u64_u32 v[16:17], s[0:1], v176, s20, v[172:173]
	s_lshl_b32 s0, s4, 7
	s_ashr_i32 s30, s34, 8
	s_and_b32 s0, s0, 0x180
	v_mad_i32_i24 v17, s3, v189, v17
	s_lshl_b32 s12, s0, 1
	s_lshl_b32 s0, s30, 6
	v_bfe_u32 v133, v132, 5, 1
	v_lshl_add_u64 v[16:17], v[16:17], 0, s[12:13]
	s_ashr_i32 s1, s0, 31
	v_lshl_add_u64 v[16:17], s[0:1], 1, v[16:17]
	v_lshlrev_b32_e32 v166, 4, v133
	v_lshl_add_u64 v[16:17], v[16:17], 0, v[166:167]
	global_load_dwordx4 v[90:93], v[16:17], off offset:3136
	global_load_dwordx4 v[96:99], v[16:17], off offset:3168
	global_load_dwordx4 v[108:111], v[16:17], off offset:3072
	global_load_dwordx4 v[112:115], v[16:17], off offset:3104
	v_cmp_lt_i32_e32 vcc, v191, v192
	s_or_b32 s0, s2, s5
	s_lshl_b32 s0, s0, 1
	v_cndmask_b32_e32 v16, v190, v191, vcc
	v_lshlrev_b32_e32 v195, 2, v16
	v_and_b32_e32 v16, 32, v132
	global_load_dwordx4 v[40:43], v16, s[62:63] offset:144
	global_load_dwordx4 v[44:47], v16, s[62:63] offset:128
	global_load_dwordx4 v[28:31], v16, s[62:63] offset:208
	global_load_dwordx4 v[36:39], v16, s[62:63] offset:192
	global_load_dwordx4 v[72:75], v16, s[62:63] offset:16
	global_load_dwordx4 v[76:79], v16, s[62:63]
	global_load_dwordx4 v[64:67], v16, s[62:63] offset:80
	global_load_dwordx4 v[68:71], v16, s[62:63] offset:64
	v_lshlrev_b32_e32 v48, 6, v133
	v_and_or_b32 v16, s2, 32, v202
	s_and_b32 s0, s0, 0x3f80
	v_lshl_or_b32 v32, v16, 7, v48
	v_or_b32_e32 v60, s0, v48
	global_load_dwordx4 v[16:19], v32, s[10:11] offset:48
	global_load_dwordx4 v[20:23], v32, s[10:11] offset:32
	global_load_dwordx4 v[24:27], v32, s[10:11] offset:16
	s_nop 0
	global_load_dwordx4 v[32:35], v32, s[10:11]
	s_nop 0
	global_load_dwordx4 v[48:51], v60, s[10:11] offset:48
	global_load_dwordx4 v[52:55], v60, s[10:11] offset:32
	global_load_dwordx4 v[56:59], v60, s[10:11] offset:16
	s_nop 0
	global_load_dwordx4 v[60:63], v60, s[10:11]
	v_mov_b32_e32 v177, s3
	v_cmp_gt_i32_e32 vcc, s21, v132
	s_waitcnt vmcnt(19)
	v_lshlrev_b32_e32 v84, 16, v93
	s_waitcnt vmcnt(18)
	v_lshlrev_b32_e32 v80, 16, v99
	v_and_b32_e32 v81, 0xffff0000, v99
	v_lshlrev_b32_e32 v82, 16, v98
	v_and_b32_e32 v83, 0xffff0000, v98
	s_waitcnt vmcnt(17)
	v_lshlrev_b32_e32 v98, 16, v111
	v_and_b32_e32 v99, 0xffff0000, v111
	v_lshlrev_b32_e32 v102, 16, v110
	v_and_b32_e32 v103, 0xffff0000, v110
	v_lshlrev_b32_e32 v110, 16, v108
	v_and_b32_e32 v111, 0xffff0000, v108
	v_lshlrev_b32_e32 v106, 16, v109
	v_and_b32_e32 v107, 0xffff0000, v109
	v_pk_mul_f32 v[148:149], v[110:111], v[110:111]
	v_pk_mul_f32 v[144:145], v[106:107], v[106:107]
	v_add_f32_e32 v148, v148, v149
	v_add_f32_e32 v144, v144, v148
	v_pk_mul_f32 v[142:143], v[102:103], v[102:103]
	v_add_f32_e32 v144, v145, v144
	v_add_f32_e32 v142, v142, v144
	v_pk_mul_f32 v[138:139], v[98:99], v[98:99]
	v_add_f32_e32 v142, v143, v142
	s_waitcnt vmcnt(16)
	v_lshlrev_b32_e32 v108, 16, v112
	v_and_b32_e32 v109, 0xffff0000, v112
	v_add_f32_e32 v138, v138, v142
	v_lshlrev_b32_e32 v104, 16, v113
	v_and_b32_e32 v105, 0xffff0000, v113
	v_pk_mul_f32 v[112:113], v[108:109], v[108:109]
	v_add_f32_e32 v138, v139, v138
	v_add_f32_e32 v112, v112, v138
	v_pk_mul_f32 v[146:147], v[104:105], v[104:105]
	v_add_f32_e32 v112, v113, v112
	v_lshlrev_b32_e32 v100, 16, v114
	v_and_b32_e32 v101, 0xffff0000, v114
	v_add_f32_e32 v112, v146, v112
	v_and_b32_e32 v85, 0xffff0000, v93
	v_lshlrev_b32_e32 v88, 16, v92
	v_and_b32_e32 v89, 0xffff0000, v92
	v_lshlrev_b32_e32 v92, 16, v91
	v_and_b32_e32 v93, 0xffff0000, v91
	v_lshlrev_b32_e32 v86, 16, v97
	v_and_b32_e32 v87, 0xffff0000, v97
	v_lshlrev_b32_e32 v94, 16, v90
	v_and_b32_e32 v95, 0xffff0000, v90
	v_lshlrev_b32_e32 v90, 16, v96
	v_and_b32_e32 v91, 0xffff0000, v96
	v_lshlrev_b32_e32 v96, 16, v115
	v_and_b32_e32 v97, 0xffff0000, v115
	v_pk_mul_f32 v[114:115], v[100:101], v[100:101]
	v_add_f32_e32 v112, v147, v112
	v_add_f32_e32 v112, v114, v112
	v_pk_mul_f32 v[140:141], v[96:97], v[96:97]
	v_add_f32_e32 v112, v115, v112
	v_add_f32_e32 v112, v140, v112
	v_pk_mul_f32 v[134:135], v[94:95], v[94:95]
	v_add_f32_e32 v112, v141, v112
	v_add_f32_e32 v112, v134, v112
	v_pk_mul_f32 v[124:125], v[92:93], v[92:93]
	v_add_f32_e32 v112, v135, v112
	v_add_f32_e32 v112, v124, v112
	v_pk_mul_f32 v[120:121], v[88:89], v[88:89]
	v_add_f32_e32 v112, v125, v112
	v_add_f32_e32 v112, v120, v112
	v_pk_mul_f32 v[116:117], v[84:85], v[84:85]
	v_add_f32_e32 v112, v121, v112
	v_add_f32_e32 v112, v116, v112
	v_pk_mul_f32 v[136:137], v[90:91], v[90:91]
	v_add_f32_e32 v112, v117, v112
	v_add_f32_e32 v112, v136, v112
	v_pk_mul_f32 v[126:127], v[86:87], v[86:87]
	v_add_f32_e32 v112, v137, v112
	v_add_f32_e32 v112, v126, v112
	v_pk_mul_f32 v[122:123], v[82:83], v[82:83]
	v_add_f32_e32 v112, v127, v112
	v_add_f32_e32 v112, v122, v112
	v_pk_mul_f32 v[118:119], v[80:81], v[80:81]
	v_add_f32_e32 v112, v123, v112
	v_add_f32_e32 v112, v118, v112
	v_add_f32_e32 v134, v119, v112
	ds_bpermute_b32 v135, v195, v134
	v_lshrrev_b32_e32 v112, 6, v188
	v_lshrrev_b32_e32 v113, 4, v190
	v_and_b32_e32 v114, 15, v190
	v_lshl_add_u32 v115, v112, 3, v113
	v_and_b32_e32 v116, 15, v115
	v_xor_b32_e32 v116, v114, v116
	v_mul_u32_u24_e32 v117, 0x1a00, v115
	v_lshl_add_u32 v181, v116, 4, v117
	v_add_u32_e32 v118, 4, v115
	v_and_b32_e32 v116, 15, v118
	v_xor_b32_e32 v116, v114, v116
	v_mul_u32_u24_e32 v118, 0x1a00, v118
	v_lshl_add_u32 v165, v116, 4, v118
	v_lshlrev_b32_e32 v116, 2, v113
	v_xor_b32_e32 v116, v114, v116
	v_lshl_add_u32 v116, v116, 4, v117
	v_add_u32_e32 v207, 0x400, v116
	v_add_u32_e32 v208, 0x6c00, v116
	s_lshl_b32 s1, s16, 8
	s_add_i32 s1, s1, 0x8000
	s_mul_i32 s2, s1, 0x1a00
	s_add_u32 s22, s8, s12
	s_addc_u32 s23, s9, 0
	s_add_u32 s22, s22, 0x1000
	s_addc_u32 s23, s23, 0
	s_add_u32 s36, s22, s2
	s_addc_u32 s37, s23, 0
	s_lshl_b32 s3, s16, 13
	s_mul_i32 s3, s3, 0x1a00
	s_add_u32 s38, s22, s3
	s_addc_u32 s39, s23, 0
	s_lshr_b32 s17, s34, 6
	s_lshl_b32 s17, s17, 11
	s_add_i32 m0, s17, 0
	s_nop 0
	global_load_lds_dwordx4 v181, s[36:37]
	s_add_i32 m0, s17, 1024
	s_nop 0
	global_load_lds_dwordx4 v165, s[36:37]
	s_add_i32 m0, s17, 16384
	s_nop 0
	global_load_lds_dwordx4 v207, s[36:37]
	s_add_i32 m0, s17, 17408
	s_nop 0
	global_load_lds_dwordx4 v208, s[36:37]
	s_add_u32 s36, s36, 0x68000
	s_addc_u32 s37, s37, 0
	s_add_i32 m0, s17, 32768
	s_nop 0
	global_load_lds_dwordx4 v181, s[36:37]
	s_add_i32 m0, s17, 33792
	s_nop 0
	global_load_lds_dwordx4 v165, s[36:37]
	s_add_i32 m0, s17, 49152
	s_nop 0
	global_load_lds_dwordx4 v207, s[36:37]
	s_add_i32 m0, s17, 50176
	s_nop 0
	global_load_lds_dwordx4 v208, s[36:37]
	s_add_u32 s36, s36, 0x68000
	s_addc_u32 s37, s37, 0
	s_add_i32 m0, s17, 65536
	s_nop 0
	global_load_lds_dwordx4 v181, s[36:37]
	s_add_i32 m0, s17, 66560
	s_nop 0
	global_load_lds_dwordx4 v165, s[36:37]
	s_add_i32 m0, s17, 81920
	s_nop 0
	global_load_lds_dwordx4 v207, s[36:37]
	s_add_i32 m0, s17, 82944
	s_nop 0
	global_load_lds_dwordx4 v208, s[36:37]
	s_add_u32 s36, s36, 0x68000
	s_addc_u32 s37, s37, 0
	v_and_b32_e32 v112, 31, v190
	v_lshrrev_b32_e32 v113, 5, v190
	v_lshrrev_b32_e32 v114, 8, v188
	v_lshl_or_b32 v113, v114, 3, v113
	v_and_b32_e32 v115, 15, v112
	v_xor_b32_e32 v113, v113, v115
	v_lshlrev_b32_e32 v112, 8, v112
	v_lshl_add_u32 v178, v113, 4, v112
	v_xor_b32_e32 v116, 2, v113
	v_lshl_add_u32 v128, v116, 4, v112
	v_xor_b32_e32 v116, 4, v113
	v_lshl_add_u32 v130, v116, 4, v112
	v_xor_b32_e32 v116, 6, v113
	v_lshl_add_u32 v131, v116, 4, v112
	v_add_u32_e32 v180, 0x10000, v178
	v_add_u32_e32 v189, 0x10000, v128
	v_add_u32_e32 v191, 0x10000, v130
	v_add_u32_e32 v192, 0x10000, v131
	v_and_b32_e32 v112, 3, v190
	v_bfe_u32 v113, v190, 2, 2
	v_bfe_u32 v114, v190, 4, 1
	v_lshrrev_b32_e32 v115, 5, v190
	v_lshlrev_b32_e32 v115, 10, v115
	v_lshl_add_u32 v115, v113, 8, v115
	v_lshl_add_u32 v115, v114, 5, v115
	v_lshl_add_u32 v115, v112, 3, v115
	v_add_u32_e32 v115, 0x4000, v115
	v_lshl_add_u32 v184, v113, 6, v115
	v_xor_b32_e32 v116, 1, v113
	v_lshl_add_u32 v185, v116, 6, v115
	v_xor_b32_e32 v116, 2, v113
	v_lshl_add_u32 v186, v116, 6, v115
	v_xor_b32_e32 v116, 3, v113
	v_lshl_add_u32 v187, v116, 6, v115
	v_add_u32_e32 v198, 0x10000, v184
	v_add_u32_e32 v199, 0x10000, v185
	v_add_u32_e32 v201, 0x10000, v186
	v_add_u32_e32 v203, 0x10000, v187
	v_mov_b32_e32 v148, 0
	v_mov_b32_e32 v149, 0
	v_mov_b32_e32 v150, 0
	v_mov_b32_e32 v151, 0
	v_lshlrev_b32_e32 v112, 4, v188
	v_add_u32_e32 v112, 0x1e000, v112
	ds_write_b128 v112, v[148:151]
	s_waitcnt vmcnt(12)
	s_waitcnt lgkmcnt(0)
	v_lshrrev_b32_e32 v136, 2, v132
	v_lshlrev_b32_e32 v179, 2, v133
	v_and_or_b32 v133, v136, 3, v179
	v_mul_u32_u24_e32 v204, 0x140, v133
	v_lshlrev_b32_e32 v133, 1, v132
	v_and_b32_e32 v205, 32, v133
	v_add_f32_e32 v133, v134, v135
	v_fmamk_f32 v133, v133, 0x3c800000, v193
	v_mul_f32_e32 v134, 0x4b800000, v133
	v_cmp_gt_f32_e32 vcc, s27, v133
	v_lshlrev_b32_e32 v132, 3, v132
	v_and_b32_e32 v206, 24, v132
	v_cndmask_b32_e32 v133, v133, v134, vcc
	v_rsq_f32_e32 v133, v133
	v_add3_u32 v197, v204, v205, v206
	v_add_u32_e32 v200, 0, v197
	s_lshl_b32 s0, s30, 7
	v_mul_f32_e32 v132, 0x45800000, v133
	v_cndmask_b32_e32 v132, v133, v132, vcc
	v_mul_f32_e32 v132, 0x3e38aa3b, v132
	v_pk_mul_f32 v[68:69], v[68:69], v[132:133] op_sel_hi:[1,0]
	v_pk_mul_f32 v[30:31], v[30:31], v[132:133] op_sel_hi:[1,0]
	v_pk_mul_f32 v[76:77], v[76:77], v[132:133] op_sel_hi:[1,0]
	v_pk_mul_f32 v[68:69], v[68:69], v[108:109]
	v_pk_mul_f32 v[30:31], v[30:31], v[80:81]
	v_mov_b32_e32 v80, v60
	v_mov_b32_e32 v81, v62
	v_mov_b32_e32 v62, v61
	v_pk_mul_f32 v[76:77], v[76:77], v[110:111]
	v_pk_mul_f32 v[70:71], v[70:71], v[132:133] op_sel_hi:[1,0]
	v_pk_mul_f32 v[60:61], v[62:63], v[68:69]
	v_pk_mul_f32 v[68:69], v[80:81], v[68:69]
	v_pk_mul_f32 v[78:79], v[78:79], v[132:133] op_sel_hi:[1,0]
	v_pk_mul_f32 v[70:71], v[70:71], v[104:105]
	v_pk_fma_f32 v[62:63], v[62:63], v[76:77], v[68:69]
	v_mov_b32_e32 v69, v58
	v_mov_b32_e32 v58, v57
	v_pk_mul_f32 v[78:79], v[78:79], v[106:107]
	v_mov_b32_e32 v68, v56
	v_pk_mul_f32 v[56:57], v[58:59], v[70:71]
	v_pk_mul_f32 v[64:65], v[64:65], v[132:133] op_sel_hi:[1,0]
	v_pk_fma_f32 v[56:57], v[68:69], v[78:79], v[56:57] neg_lo:[0,0,1] neg_hi:[0,0,1]
	v_pk_mul_f32 v[68:69], v[68:69], v[70:71]
	v_pk_mul_f32 v[72:73], v[72:73], v[132:133] op_sel_hi:[1,0]
	v_pk_mul_f32 v[64:65], v[64:65], v[100:101]
	v_pk_fma_f32 v[58:59], v[58:59], v[78:79], v[68:69]
	v_mov_b32_e32 v68, v52
	v_mov_b32_e32 v69, v54
	v_mov_b32_e32 v54, v53
	v_pk_mul_f32 v[72:73], v[72:73], v[102:103]
	v_pk_mul_f32 v[66:67], v[66:67], v[132:133] op_sel_hi:[1,0]
	v_pk_mul_f32 v[52:53], v[54:55], v[64:65]
	v_pk_mul_f32 v[64:65], v[68:69], v[64:65]
	v_pk_mul_f32 v[74:75], v[74:75], v[132:133] op_sel_hi:[1,0]
	v_pk_mul_f32 v[66:67], v[66:67], v[96:97]
	v_pk_fma_f32 v[54:55], v[54:55], v[72:73], v[64:65]
	v_mov_b32_e32 v65, v50
	v_mov_b32_e32 v50, v49
	v_pk_mul_f32 v[74:75], v[74:75], v[98:99]
	v_mov_b32_e32 v64, v48
	v_pk_mul_f32 v[48:49], v[50:51], v[66:67]
	v_pk_mul_f32 v[36:37], v[36:37], v[132:133] op_sel_hi:[1,0]
	v_pk_fma_f32 v[48:49], v[74:75], v[64:65], v[48:49] neg_lo:[0,0,1] neg_hi:[0,0,1]
	v_pk_mul_f32 v[64:65], v[64:65], v[66:67]
	v_pk_mul_f32 v[44:45], v[44:45], v[132:133] op_sel_hi:[1,0]
	v_pk_mul_f32 v[36:37], v[36:37], v[90:91]
	v_pk_fma_f32 v[50:51], v[50:51], v[74:75], v[64:65]
	v_mov_b32_e32 v64, v32
	v_mov_b32_e32 v65, v34
	v_mov_b32_e32 v34, v33
	v_pk_mul_f32 v[44:45], v[44:45], v[94:95]
	v_pk_mul_f32 v[38:39], v[38:39], v[132:133] op_sel_hi:[1,0]
	v_pk_mul_f32 v[32:33], v[36:37], v[34:35]
	v_pk_mul_f32 v[36:37], v[36:37], v[64:65]
	v_pk_mul_f32 v[46:47], v[46:47], v[132:133] op_sel_hi:[1,0]
	v_pk_mul_f32 v[38:39], v[38:39], v[86:87]
	v_pk_fma_f32 v[34:35], v[44:45], v[34:35], v[36:37]
	v_mov_b32_e32 v37, v26
	v_mov_b32_e32 v26, v25
	v_pk_mul_f32 v[46:47], v[46:47], v[92:93]
	v_mov_b32_e32 v36, v24
	v_pk_mul_f32 v[24:25], v[38:39], v[26:27]
	v_pk_mul_f32 v[28:29], v[28:29], v[132:133] op_sel_hi:[1,0]
	v_pk_fma_f32 v[24:25], v[46:47], v[36:37], v[24:25] neg_lo:[0,0,1] neg_hi:[0,0,1]
	v_pk_mul_f32 v[36:37], v[38:39], v[36:37]
	v_pk_mul_f32 v[40:41], v[40:41], v[132:133] op_sel_hi:[1,0]
	v_pk_mul_f32 v[28:29], v[28:29], v[82:83]
	v_pk_fma_f32 v[26:27], v[46:47], v[26:27], v[36:37]
	v_mov_b32_e32 v36, v20
	v_mov_b32_e32 v37, v22
	v_mov_b32_e32 v22, v21
	v_pk_mul_f32 v[40:41], v[40:41], v[88:89]
	v_pk_mul_f32 v[20:21], v[28:29], v[22:23]
	v_pk_mul_f32 v[28:29], v[28:29], v[36:37]
	v_pk_mul_f32 v[42:43], v[42:43], v[132:133] op_sel_hi:[1,0]
	v_pk_fma_f32 v[22:23], v[40:41], v[22:23], v[28:29]
	v_mov_b32_e32 v29, v18
	v_mov_b32_e32 v18, v17
	v_pk_mul_f32 v[42:43], v[42:43], v[84:85]
	v_mov_b32_e32 v28, v16
	v_pk_mul_f32 v[16:17], v[30:31], v[18:19]
	v_pk_fma_f32 v[60:61], v[80:81], v[76:77], v[60:61] neg_lo:[0,0,1] neg_hi:[0,0,1]
	v_pk_fma_f32 v[16:17], v[42:43], v[28:29], v[16:17] neg_lo:[0,0,1] neg_hi:[0,0,1]
	v_pk_mul_f32 v[28:29], v[30:31], v[28:29]
	v_pk_fma_f32 v[52:53], v[68:69], v[72:73], v[52:53] neg_lo:[0,0,1] neg_hi:[0,0,1]
	v_pk_fma_f32 v[32:33], v[44:45], v[64:65], v[32:33] neg_lo:[0,0,1] neg_hi:[0,0,1]
	v_pk_fma_f32 v[20:21], v[40:41], v[36:37], v[20:21] neg_lo:[0,0,1] neg_hi:[0,0,1]
	v_pk_fma_f32 v[18:19], v[42:43], v[18:19], v[28:29]
	v_cvt_pk_bf16_f32 v140, v60, v61
	v_cvt_pk_bf16_f32 v141, v56, v57
	v_cvt_pk_bf16_f32 v142, v52, v53
	v_cvt_pk_bf16_f32 v143, v48, v49
	v_cvt_pk_bf16_f32 v144, v62, v63
	v_cvt_pk_bf16_f32 v145, v58, v59
	v_cvt_pk_bf16_f32 v146, v54, v55
	v_cvt_pk_bf16_f32 v147, v50, v51
	v_cvt_pk_bf16_f32 v136, v32, v33
	v_cvt_pk_bf16_f32 v137, v24, v25
	v_cvt_pk_bf16_f32 v138, v20, v21
	v_cvt_pk_bf16_f32 v139, v16, v17
	v_cvt_pk_bf16_f32 v132, v34, v35
	v_cvt_pk_bf16_f32 v133, v26, v27
	v_cvt_pk_bf16_f32 v134, v22, v23
	v_cvt_pk_bf16_f32 v135, v18, v19
	v_mov_b32_e32 v64, 0
	v_mov_b32_e32 v65, 0
	v_mov_b32_e32 v66, 0
	v_mov_b32_e32 v67, 0
	v_mov_b32_e32 v68, 0
	v_mov_b32_e32 v69, 0
	v_mov_b32_e32 v70, 0
	v_mov_b32_e32 v71, 0
	v_mov_b32_e32 v72, 0
	v_mov_b32_e32 v73, 0
	v_mov_b32_e32 v74, 0
	v_mov_b32_e32 v75, 0
	v_mov_b32_e32 v76, 0
	v_mov_b32_e32 v77, 0
	v_mov_b32_e32 v78, 0
	v_mov_b32_e32 v79, 0
	v_mov_b32_e32 v48, 0
	v_mov_b32_e32 v49, 0
	v_mov_b32_e32 v50, 0
	v_mov_b32_e32 v51, 0
	v_mov_b32_e32 v52, 0
	v_mov_b32_e32 v53, 0
	v_mov_b32_e32 v54, 0
	v_mov_b32_e32 v55, 0
	v_mov_b32_e32 v56, 0
	v_mov_b32_e32 v57, 0
	v_mov_b32_e32 v58, 0
	v_mov_b32_e32 v59, 0
	v_mov_b32_e32 v60, 0
	v_mov_b32_e32 v61, 0
	v_mov_b32_e32 v62, 0
	v_mov_b32_e32 v63, 0
	v_mov_b32_e32 v32, 0
	v_mov_b32_e32 v33, 0
	v_mov_b32_e32 v34, 0
	v_mov_b32_e32 v35, 0
	v_mov_b32_e32 v36, 0
	v_mov_b32_e32 v37, 0
	v_mov_b32_e32 v38, 0
	v_mov_b32_e32 v39, 0
	v_mov_b32_e32 v40, 0
	v_mov_b32_e32 v41, 0
	v_mov_b32_e32 v42, 0
	v_mov_b32_e32 v43, 0
	v_mov_b32_e32 v44, 0
	v_mov_b32_e32 v45, 0
	v_mov_b32_e32 v46, 0
	v_mov_b32_e32 v47, 0
	v_mov_b32_e32 v16, 0
	v_mov_b32_e32 v17, 0
	v_mov_b32_e32 v18, 0
	v_mov_b32_e32 v19, 0
	v_mov_b32_e32 v20, 0
	v_mov_b32_e32 v21, 0
	v_mov_b32_e32 v22, 0
	v_mov_b32_e32 v23, 0
	v_mov_b32_e32 v24, 0
	v_mov_b32_e32 v25, 0
	v_mov_b32_e32 v26, 0
	v_mov_b32_e32 v27, 0
	v_mov_b32_e32 v28, 0
	v_mov_b32_e32 v29, 0
	v_mov_b32_e32 v30, 0
	v_mov_b32_e32 v31, 0
	v_mov_b32_e32 v80, 0xf149f2ca
	v_mov_b32_e32 v81, 0xf149f2ca
	v_mov_b32_e32 v82, 0xf149f2ca
	v_mov_b32_e32 v83, 0xf149f2ca
	v_mov_b32_e32 v84, 0xf149f2ca
	v_mov_b32_e32 v85, 0xf149f2ca
	v_mov_b32_e32 v86, 0xf149f2ca
	v_mov_b32_e32 v87, 0xf149f2ca
	v_mov_b32_e32 v88, 0xf149f2ca
	v_mov_b32_e32 v89, 0xf149f2ca
	v_mov_b32_e32 v90, 0xf149f2ca
	v_mov_b32_e32 v91, 0xf149f2ca
	v_mov_b32_e32 v92, 0xf149f2ca
	v_mov_b32_e32 v93, 0xf149f2ca
	v_mov_b32_e32 v94, 0xf149f2ca
	v_mov_b32_e32 v95, 0xf149f2ca
	v_mov_b32_e32 v225, 0
	v_mov_b32_e32 v166, 0
	v_mov_b32_e32 v175, 0
	v_mov_b32_e32 v202, 0
	s_waitcnt vmcnt(8)
	s_barrier
	ds_read_b128 v[112:115], v178
	ds_read_b128 v[116:119], v128
	ds_read_b128 v[120:123], v130
	ds_read_b128 v[124:127], v131
	s_mov_b32 s16, 0
	s_cmpk_lt_u32 s17, 0x2000
	s_cbranch_scc0 .Latt_prio_done
	s_setprio 1
